# instruction selection in the dilated slab loop (softmax exponent as one fma per element, P tile bf16 conversion via v_cvt_pk_bf16_f32 pairs) plus the last row-stat store pair merge, on top of the prev
# baseline (speedup 1.0000x reference)
.Ldil_skipv:
	s_mov_b64 s[52:53], 0
	s_mov_b32 s98, 0x3fb8aa3b
	v_lshl_add_u32 v80, v60, 2, v36
	v_mov_b32_e32 v78, 0xf149f2ca
	s_and_saveexec_b64 s[28:29], s[30:31]
	s_cbranch_execz .LBB0_1989
	ds_read_b32 v78, v80 offset:576
	s_waitcnt lgkmcnt(0)
	v_add_f32_e32 v78, v32, v78

.LBB0_2005:
	s_or_b64 exec, exec, s[44:45]
	v_max_f32_e32 v4, v78, v78
	v_max_f32_e32 v4, 0xf149f2ca, v4
	v_max3_f32 v4, v4, v77, v32
	v_max3_f32 v4, v4, v28, v87
	v_max3_f32 v4, v4, v79, v8
	v_max3_f32 v4, v4, v0, v49
	v_mov_b32_e32 v12, v37
	v_cmp_lt_f32_e32 vcc, s69, v78
	s_nop 0
	v_mov_b32_dpp v12, v4 row_ror:8 row_mask:0xf bank_mask:0xf
	v_max_f32_e32 v12, v12, v12
	v_max_f32_e32 v4, v4, v12
	v_mov_b32_e32 v12, v37
	s_nop 1
	v_mov_b32_dpp v12, v4 row_ror:4 row_mask:0xf bank_mask:0xf
	v_max_f32_e32 v12, v12, v12
	v_max_f32_e32 v4, v4, v12
	v_mov_b32_e32 v12, v37
	s_nop 1
	v_mov_b32_dpp v12, v4 row_ror:2 row_mask:0xf bank_mask:0xf
	v_max_f32_e32 v12, v12, v12
	v_max_f32_e32 v4, v4, v12
	v_mov_b32_e32 v12, v37
	s_nop 1
	v_mov_b32_dpp v12, v4 row_ror:1 row_mask:0xf bank_mask:0xf
	v_max_f32_e32 v12, v12, v12
	v_max_f32_e32 v4, v4, v12
	v_mul_f32_e32 v218, 0xbfb8aa3b, v4
	v_fma_f32 v12, v78, s98, v218
	v_fma_f32 v16, v77, s98, v218
	v_exp_f32_e32 v12, v12
	v_fma_f32 v24, v32, s98, v218
	v_exp_f32_e32 v16, v16
	v_exp_f32_e32 v24, v24
	v_cndmask_b32_e32 v12, 0, v12, vcc
	v_cmp_lt_f32_e32 vcc, s69, v77
	v_add_f32_e32 v20, 0, v12
	v_fma_f32 v78, v8, s98, v218
	v_cndmask_b32_e32 v16, 0, v16, vcc
	v_cmp_lt_f32_e32 vcc, s69, v32
	v_add_f32_e32 v77, v16, v20
	v_cndmask_b32_e32 v20, 0, v24, vcc
	v_fma_f32 v24, v28, s98, v218
	v_add_f32_e32 v32, v20, v77
	v_fma_f32 v77, v87, s98, v218
	v_exp_f32_e32 v24, v24
	v_exp_f32_e32 v77, v77
	v_cmp_lt_f32_e32 vcc, s69, v28
	v_exp_f32_e32 v78, v78
	s_nop 0
	v_cndmask_b32_e32 v24, 0, v24, vcc
	v_cmp_lt_f32_e32 vcc, s69, v87
	v_add_f32_e32 v32, v24, v32
	v_subrev_u32_e32 v87, s80, v76
	v_cndmask_b32_e32 v28, 0, v77, vcc
	v_add_f32_e32 v77, v28, v32
	v_fma_f32 v32, v79, s98, v218
	v_exp_f32_e32 v32, v32
	v_cmp_lt_f32_e32 vcc, s69, v79
	s_nop 1
	v_cndmask_b32_e32 v32, 0, v32, vcc
	v_cmp_lt_f32_e32 vcc, s69, v8
	v_add_f32_e32 v79, v32, v77
	s_nop 0
	v_cndmask_b32_e32 v77, 0, v78, vcc
	v_fma_f32 v78, v0, s98, v218
	v_add_f32_e32 v8, v77, v79
	v_fma_f32 v79, v49, s98, v218
	v_exp_f32_e32 v78, v78
	v_exp_f32_e32 v79, v79
	v_cmp_lt_f32_e32 vcc, s69, v0
	s_nop 1
	v_cndmask_b32_e32 v78, 0, v78, vcc
	v_cmp_lt_f32_e32 vcc, s69, v49
	v_add_f32_e32 v0, v78, v8
	s_nop 0
	v_cndmask_b32_e32 v79, 0, v79, vcc
	v_add_f32_e32 v0, v79, v0
	s_nop 1
	v_add_f32_dpp v0, v0, v0 row_ror:8 row_mask:0xf bank_mask:0xf bound_ctrl:1
	s_nop 1
	v_add_f32_dpp v0, v0, v0 row_ror:4 row_mask:0xf bank_mask:0xf bound_ctrl:1
	s_nop 1
	v_add_f32_dpp v0, v0, v0 row_ror:2 row_mask:0xf bank_mask:0xf bound_ctrl:1
	s_nop 1
	v_add_f32_dpp v49, v0, v0 row_ror:1 row_mask:0xf bank_mask:0xf bound_ctrl:1
	v_mov_b32_e32 v240, v49
	v_cmp_gt_f32_e32 vcc, s56, v49
	s_nop 1
	v_cndmask_b32_e64 v0, 0, 32, vcc
	v_ldexp_f32 v0, v49, v0
	v_log_f32_e32 v8, v0
	v_or_b32_e32 v0, v75, v52
	v_mul_f32_e32 v89, 0x3f317217, v8
	v_fma_f32 v89, v8, s57, -v89
	v_fmac_f32_e32 v89, 0x3377d1cf, v8
	v_fmac_f32_e32 v89, 0x3f317217, v8
	v_cmp_lt_f32_e64 s[44:45], |v8|, s58
	s_nop 1
	v_cndmask_b32_e64 v8, v8, v89, s[44:45]
	v_cndmask_b32_e32 v89, 0, v55, vcc
	v_sub_f32_e32 v8, v8, v89
	v_add_f32_e32 v4, v4, v8
	v_lshl_add_u32 v89, v0, v73, v87
	s_mov_b64 s[44:45], -1
	s_and_b64 vcc, exec, s[52:53]
	s_cbranch_vccz .LBB0_2007
	v_lshlrev_b32_e32 v8, 2, v89
	v_add_u32_e32 v90, 48, v8
	ds_read_b32 v8, v8 offset:3632
	ds_read2st64_b32 v[90:91], v90 offset0:6 offset1:10
	s_waitcnt lgkmcnt(0)
	v_max3_f32 v92, v90, v91, v8
	v_sub_f32_e32 v90, v90, v92
	v_sub_f32_e32 v91, v91, v92
	v_mul_f32_e32 v90, 0x3fb8aa3b, v90
	v_mul_f32_e32 v91, 0x3fb8aa3b, v91
	v_exp_f32_e32 v90, v90
	v_exp_f32_e32 v91, v91
	v_sub_f32_e32 v8, v8, v92
	v_mul_f32_e32 v8, 0x3fb8aa3b, v8
	v_exp_f32_e32 v8, v8
	v_add_f32_e32 v90, v90, v91
	v_sub_f32_e32 v91, v4, v92
	v_mul_f32_e32 v91, 0x3fb8aa3b, v91
	v_exp_f32_e32 v91, v91
	v_add_f32_e32 v8, v8, v90
	v_mul_f32_e32 v8, v49, v8
	v_div_scale_f32 v49, s[44:45], v8, v8, v91
	v_rcp_f32_e32 v90, v49
	s_mov_b64 s[44:45], 0
	v_fma_f32 v92, -v49, v90, 1.0
	v_fmac_f32_e32 v90, v92, v90
	v_div_scale_f32 v92, vcc, v91, v8, v91
	v_mul_f32_e32 v93, v92, v90
	v_fma_f32 v94, -v49, v93, v92
	v_fmac_f32_e32 v93, v94, v90
	v_fma_f32 v49, -v49, v93, v92
	v_div_fmas_f32 v49, v49, v90, v93
	v_div_fixup_f32 v8, v49, v8, v91

.LBB0_2029:
	s_or_b64 exec, exec, s[44:45]
	v_max_f32_e32 v1, v89, v89
	v_max_f32_e32 v1, 0xf149f2ca, v1
	v_max3_f32 v1, v1, v4, v33
	v_max3_f32 v1, v1, v29, v90
	v_max3_f32 v1, v1, v25, v91
	v_max3_f32 v1, v1, v9, v92
	v_mov_b32_e32 v5, v37
	v_cmp_lt_f32_e32 vcc, s69, v89
	s_mov_b64 s[46:47], -1
	v_mov_b32_dpp v5, v1 row_ror:8 row_mask:0xf bank_mask:0xf
	v_max_f32_e32 v5, v5, v5
	v_max_f32_e32 v1, v1, v5
	v_mov_b32_e32 v5, v37
	s_nop 1
	v_mov_b32_dpp v5, v1 row_ror:4 row_mask:0xf bank_mask:0xf
	v_max_f32_e32 v5, v5, v5
	v_max_f32_e32 v1, v1, v5
	v_mov_b32_e32 v5, v37
	s_nop 1
	v_mov_b32_dpp v5, v1 row_ror:2 row_mask:0xf bank_mask:0xf
	v_max_f32_e32 v5, v5, v5
	v_max_f32_e32 v1, v1, v5
	v_mov_b32_e32 v5, v37
	s_nop 1
	v_mov_b32_dpp v5, v1 row_ror:1 row_mask:0xf bank_mask:0xf
	v_max_f32_e32 v5, v5, v5
	v_max_f32_e32 v93, v1, v5
	v_mul_f32_e32 v218, 0xbfb8aa3b, v93
	v_fma_f32 v1, v89, s98, v218
	v_fma_f32 v5, v4, s98, v218
	v_exp_f32_e32 v1, v1
	v_fma_f32 v17, v33, s98, v218
	v_exp_f32_e32 v5, v5
	v_exp_f32_e32 v17, v17
	v_cndmask_b32_e32 v1, 0, v1, vcc
	v_cmp_lt_f32_e32 vcc, s69, v4
	v_add_f32_e32 v13, 0, v1
	v_fma_f32 v21, v90, s98, v218
	v_cndmask_b32_e32 v5, 0, v5, vcc
	v_cmp_lt_f32_e32 vcc, s69, v33
	v_add_f32_e32 v4, v5, v13
	v_cndmask_b32_e32 v13, 0, v17, vcc
	v_fma_f32 v17, v29, s98, v218
	v_exp_f32_e32 v17, v17
	v_cmp_lt_f32_e32 vcc, s69, v29
	v_fma_f32 v29, v25, s98, v218
	v_exp_f32_e32 v21, v21
	v_fma_f32 v33, v91, s98, v218
	v_exp_f32_e32 v29, v29
	v_exp_f32_e32 v33, v33
	v_cndmask_b32_e32 v17, 0, v17, vcc
	v_cmp_lt_f32_e32 vcc, s69, v90
	v_fma_f32 v36, v92, s98, v218
	v_add_f32_e32 v4, v13, v4
	v_cndmask_b32_e32 v21, 0, v21, vcc
	v_cmp_lt_f32_e32 vcc, s69, v25
	v_add_f32_e32 v4, v17, v4
	v_cndmask_b32_e32 v25, 0, v29, vcc
	v_cmp_lt_f32_e32 vcc, s69, v91
	v_exp_f32_e32 v36, v36
	v_add_f32_e32 v4, v21, v4
	v_cndmask_b32_e32 v29, 0, v33, vcc
	v_fma_f32 v33, v9, s98, v218
	v_exp_f32_e32 v33, v33
	v_add_f32_e32 v4, v25, v4
	v_cmp_lt_f32_e32 vcc, s69, v9
	v_add_f32_e32 v4, v29, v4
	s_nop 0
	v_cndmask_b32_e32 v33, 0, v33, vcc
	v_cmp_lt_f32_e32 vcc, s69, v92
	v_add_f32_e32 v4, v33, v4
	s_nop 0
	v_cndmask_b32_e32 v36, 0, v36, vcc
	v_add_f32_e32 v4, v36, v4
	s_nop 1
	v_add_f32_dpp v4, v4, v4 row_ror:8 row_mask:0xf bank_mask:0xf bound_ctrl:1
	s_nop 1
	v_add_f32_dpp v4, v4, v4 row_ror:4 row_mask:0xf bank_mask:0xf bound_ctrl:1
	s_nop 1
	v_add_f32_dpp v4, v4, v4 row_ror:2 row_mask:0xf bank_mask:0xf bound_ctrl:1
	s_nop 1
	v_add_f32_dpp v91, v4, v4 row_ror:1 row_mask:0xf bank_mask:0xf bound_ctrl:1
	v_mov_b32_e32 v241, v91
	v_cmp_gt_f32_e32 vcc, s56, v91
	s_nop 1
	v_cndmask_b32_e64 v4, 0, 32, vcc
	v_ldexp_f32 v4, v91, v4
	v_log_f32_e32 v4, v4
	s_nop 0
	v_mul_f32_e32 v9, 0x3f317217, v4
	v_fma_f32 v9, v4, s57, -v9
	v_fmac_f32_e32 v9, 0x3377d1cf, v4
	v_fmac_f32_e32 v9, 0x3f317217, v4
	v_cmp_lt_f32_e64 s[44:45], |v4|, s58
	s_nop 1
	v_cndmask_b32_e64 v4, v4, v9, s[44:45]
	v_cndmask_b32_e32 v9, 0, v55, vcc
	v_sub_f32_e32 v4, v4, v9
	v_add_f32_e32 v89, v93, v4
	v_or_b32_e32 v4, 1, v0
	v_cndmask_b32_e64 v9, 0, 1, s[52:53]
	v_lshl_add_u32 v90, v4, v73, v87
	v_cmp_ne_u32_e64 s[44:45], 1, v9
	s_andn2_b64 vcc, exec, s[52:53]
	s_cbranch_vccnz .LBB0_2031
	v_lshlrev_b32_e32 v9, 2, v90
	v_add_u32_e32 v92, 48, v9
	ds_read_b32 v9, v9 offset:3632
	ds_read2st64_b32 v[92:93], v92 offset0:6 offset1:10
	s_waitcnt lgkmcnt(0)
	v_max3_f32 v94, v92, v93, v9
	v_sub_f32_e32 v92, v92, v94
	v_sub_f32_e32 v93, v93, v94
	v_mul_f32_e32 v92, 0x3fb8aa3b, v92
	v_mul_f32_e32 v93, 0x3fb8aa3b, v93
	v_exp_f32_e32 v92, v92
	v_exp_f32_e32 v93, v93
	v_sub_f32_e32 v9, v9, v94
	v_mul_f32_e32 v9, 0x3fb8aa3b, v9
	v_exp_f32_e32 v9, v9
	v_add_f32_e32 v92, v92, v93
	v_sub_f32_e32 v93, v89, v94
	v_mul_f32_e32 v93, 0x3fb8aa3b, v93
	v_exp_f32_e32 v93, v93
	v_add_f32_e32 v9, v9, v92
	v_mul_f32_e32 v9, v91, v9
	v_div_scale_f32 v91, s[46:47], v9, v9, v93
	v_rcp_f32_e32 v92, v91
	s_mov_b64 s[46:47], 0
	v_fma_f32 v94, -v91, v92, 1.0
	v_fmac_f32_e32 v92, v94, v92
	v_div_scale_f32 v94, vcc, v93, v9, v93
	v_mul_f32_e32 v95, v94, v92
	v_fma_f32 v96, -v91, v95, v94
	v_fmac_f32_e32 v95, v96, v92
	v_fma_f32 v91, -v91, v95, v94
	v_div_fmas_f32 v91, v91, v92, v95
	v_div_fixup_f32 v9, v91, v9, v93

.LBB0_2051:
	s_or_b64 exec, exec, s[46:47]
	v_max_f32_e32 v6, v90, v90
	v_max_f32_e32 v6, 0xf149f2ca, v6
	v_max3_f32 v6, v6, v89, v91
	v_max3_f32 v6, v6, v30, v92
	v_max3_f32 v6, v6, v34, v10
	v_max3_f32 v6, v6, v2, v93
	v_mov_b32_e32 v14, v37
	v_cmp_lt_f32_e32 vcc, s69, v90
	s_nop 0
	v_mov_b32_dpp v14, v6 row_ror:8 row_mask:0xf bank_mask:0xf
	v_max_f32_e32 v14, v14, v14
	v_max_f32_e32 v6, v6, v14
	v_mov_b32_e32 v14, v37
	s_nop 1
	v_mov_b32_dpp v14, v6 row_ror:4 row_mask:0xf bank_mask:0xf
	v_max_f32_e32 v14, v14, v14
	v_max_f32_e32 v6, v6, v14
	v_mov_b32_e32 v14, v37
	s_nop 1
	v_mov_b32_dpp v14, v6 row_ror:2 row_mask:0xf bank_mask:0xf
	v_max_f32_e32 v14, v14, v14
	v_max_f32_e32 v6, v6, v14
	v_mov_b32_e32 v14, v37
	s_nop 1
	v_mov_b32_dpp v14, v6 row_ror:1 row_mask:0xf bank_mask:0xf
	v_max_f32_e32 v14, v14, v14
	v_max_f32_e32 v6, v6, v14
	v_mul_f32_e32 v218, 0xbfb8aa3b, v6
	v_fma_f32 v14, v90, s98, v218
	v_fma_f32 v18, v89, s98, v218
	v_exp_f32_e32 v14, v14
	v_fma_f32 v26, v91, s98, v218
	v_exp_f32_e32 v18, v18
	v_exp_f32_e32 v26, v26
	v_cndmask_b32_e32 v14, 0, v14, vcc
	v_cmp_lt_f32_e32 vcc, s69, v89
	v_add_f32_e32 v22, 0, v14
	v_fma_f32 v90, v92, s98, v218
	v_cndmask_b32_e32 v18, 0, v18, vcc
	v_cmp_lt_f32_e32 vcc, s69, v91
	v_add_f32_e32 v89, v18, v22
	v_cndmask_b32_e32 v22, 0, v26, vcc
	v_fma_f32 v26, v30, s98, v218
	v_exp_f32_e32 v26, v26
	v_exp_f32_e32 v90, v90
	v_cmp_lt_f32_e32 vcc, s69, v30
	v_fma_f32 v91, v10, s98, v218
	v_cndmask_b32_e32 v26, 0, v26, vcc
	v_cmp_lt_f32_e32 vcc, s69, v92
	v_exp_f32_e32 v91, v91
	v_add_f32_e32 v89, v22, v89
	v_cndmask_b32_e32 v30, 0, v90, vcc
	v_fma_f32 v90, v34, s98, v218
	v_exp_f32_e32 v90, v90
	v_add_f32_e32 v89, v26, v89
	v_cmp_lt_f32_e32 vcc, s69, v34
	v_add_f32_e32 v89, v30, v89
	s_nop 0
	v_cndmask_b32_e32 v34, 0, v90, vcc
	v_cmp_lt_f32_e32 vcc, s69, v10
	v_add_f32_e32 v90, v34, v89
	s_nop 0
	v_cndmask_b32_e32 v89, 0, v91, vcc
	v_add_f32_e32 v10, v89, v90
	v_fma_f32 v90, v2, s98, v218
	v_fma_f32 v91, v93, s98, v218
	v_exp_f32_e32 v90, v90
	v_exp_f32_e32 v91, v91
	v_cmp_lt_f32_e32 vcc, s69, v2
	s_nop 1
	v_cndmask_b32_e32 v90, 0, v90, vcc
	v_cmp_lt_f32_e32 vcc, s69, v93
	v_add_f32_e32 v2, v90, v10
	s_nop 0
	v_cndmask_b32_e32 v91, 0, v91, vcc
	v_add_f32_e32 v2, v91, v2
	s_nop 1
	v_add_f32_dpp v2, v2, v2 row_ror:8 row_mask:0xf bank_mask:0xf bound_ctrl:1
	s_nop 1
	v_add_f32_dpp v2, v2, v2 row_ror:4 row_mask:0xf bank_mask:0xf bound_ctrl:1
	s_nop 1
	v_add_f32_dpp v2, v2, v2 row_ror:2 row_mask:0xf bank_mask:0xf bound_ctrl:1
	s_nop 1
	v_add_f32_dpp v93, v2, v2 row_ror:1 row_mask:0xf bank_mask:0xf bound_ctrl:1
	v_mov_b32_e32 v242, v93
	v_cmp_gt_f32_e32 vcc, s56, v93
	s_nop 1
	v_cndmask_b32_e64 v2, 0, 32, vcc
	v_ldexp_f32 v2, v93, v2
	v_log_f32_e32 v2, v2
	s_nop 0
	v_mul_f32_e32 v10, 0x3f317217, v2
	v_fma_f32 v10, v2, s57, -v10
	v_fmac_f32_e32 v10, 0x3377d1cf, v2
	v_fmac_f32_e32 v10, 0x3f317217, v2
	v_cmp_lt_f32_e64 s[46:47], |v2|, s58
	s_nop 1
	v_cndmask_b32_e64 v2, v2, v10, s[46:47]
	v_cndmask_b32_e32 v10, 0, v55, vcc
	v_sub_f32_e32 v2, v2, v10
	v_add_f32_e32 v6, v6, v2
	v_or_b32_e32 v2, 2, v0
	v_lshl_add_u32 v92, v2, v73, v87
	s_and_b64 vcc, exec, s[44:45]
	s_mov_b64 s[46:47], -1
	s_cbranch_vccnz .LBB0_2053
	v_lshlrev_b32_e32 v10, 2, v92
	v_add_u32_e32 v94, 48, v10
	ds_read_b32 v10, v10 offset:3632
	ds_read2st64_b32 v[94:95], v94 offset0:6 offset1:10
	s_waitcnt lgkmcnt(0)
	v_max3_f32 v96, v94, v95, v10
	v_sub_f32_e32 v94, v94, v96
	v_sub_f32_e32 v95, v95, v96
	v_mul_f32_e32 v94, 0x3fb8aa3b, v94
	v_mul_f32_e32 v95, 0x3fb8aa3b, v95
	v_exp_f32_e32 v94, v94
	v_exp_f32_e32 v95, v95
	v_sub_f32_e32 v10, v10, v96
	v_mul_f32_e32 v10, 0x3fb8aa3b, v10
	v_exp_f32_e32 v10, v10
	v_add_f32_e32 v94, v94, v95
	v_sub_f32_e32 v95, v6, v96
	v_mul_f32_e32 v95, 0x3fb8aa3b, v95
	v_exp_f32_e32 v95, v95
	v_add_f32_e32 v10, v10, v94
	v_mul_f32_e32 v10, v93, v10
	v_div_scale_f32 v93, s[46:47], v10, v10, v95
	v_rcp_f32_e32 v94, v93
	s_mov_b64 s[46:47], 0
	v_fma_f32 v96, -v93, v94, 1.0
	v_fmac_f32_e32 v94, v96, v94
	v_div_scale_f32 v96, vcc, v95, v10, v95
	v_mul_f32_e32 v97, v96, v94
	v_fma_f32 v98, -v93, v97, v96
	v_fmac_f32_e32 v97, v98, v94
	v_fma_f32 v93, -v93, v97, v96
	v_div_fmas_f32 v93, v93, v94, v97
	v_div_fixup_f32 v10, v93, v10, v95

.LBB0_2073:
	s_or_b64 exec, exec, s[26:27]
	v_max_f32_e32 v3, v92, v92
	v_max_f32_e32 v3, 0xf149f2ca, v3
	v_max3_f32 v3, v3, v6, v35
	v_max3_f32 v3, v3, v31, v80
	v_max3_f32 v3, v3, v27, v81
	v_max3_f32 v3, v3, v11, v82
	v_mov_b32_e32 v7, v37
	v_cmp_lt_f32_e32 vcc, s69, v92
	s_nop 0
	v_mov_b32_dpp v7, v3 row_ror:8 row_mask:0xf bank_mask:0xf
	v_max_f32_e32 v7, v7, v7
	v_max_f32_e32 v3, v3, v7
	v_mov_b32_e32 v7, v37
	s_nop 1
	v_mov_b32_dpp v7, v3 row_ror:4 row_mask:0xf bank_mask:0xf
	v_max_f32_e32 v7, v7, v7
	v_max_f32_e32 v3, v3, v7
	v_mov_b32_e32 v7, v37
	s_nop 1
	v_mov_b32_dpp v7, v3 row_ror:2 row_mask:0xf bank_mask:0xf
	v_max_f32_e32 v7, v7, v7
	v_max_f32_e32 v3, v3, v7
	v_mov_b32_e32 v7, v37
	s_nop 1
	v_mov_b32_dpp v7, v3 row_ror:1 row_mask:0xf bank_mask:0xf
	v_max_f32_e32 v7, v7, v7
	v_max_f32_e32 v83, v3, v7
	v_mul_f32_e32 v218, 0xbfb8aa3b, v83
	v_fma_f32 v3, v92, s98, v218
	v_fma_f32 v7, v6, s98, v218
	v_exp_f32_e32 v3, v3
	v_fma_f32 v19, v35, s98, v218
	v_exp_f32_e32 v7, v7
	v_exp_f32_e32 v19, v19
	v_cndmask_b32_e32 v3, 0, v3, vcc
	v_cmp_lt_f32_e32 vcc, s69, v6
	v_add_f32_e32 v15, 0, v3
	v_fma_f32 v23, v80, s98, v218
	v_cndmask_b32_e32 v7, 0, v7, vcc
	v_cmp_lt_f32_e32 vcc, s69, v35
	v_add_f32_e32 v6, v7, v15
	v_cndmask_b32_e32 v15, 0, v19, vcc
	v_fma_f32 v19, v31, s98, v218
	v_exp_f32_e32 v19, v19
	v_cmp_lt_f32_e32 vcc, s69, v31
	v_fma_f32 v31, v27, s98, v218
	v_exp_f32_e32 v23, v23
	v_fma_f32 v35, v81, s98, v218
	v_exp_f32_e32 v31, v31
	v_exp_f32_e32 v35, v35
	v_cndmask_b32_e32 v19, 0, v19, vcc
	v_cmp_lt_f32_e32 vcc, s69, v80
	v_fma_f32 v49, v82, s98, v218
	v_add_f32_e32 v6, v15, v6
	v_cndmask_b32_e32 v23, 0, v23, vcc
	v_cmp_lt_f32_e32 vcc, s69, v27
	v_add_f32_e32 v6, v19, v6
	v_cndmask_b32_e32 v27, 0, v31, vcc
	v_cmp_lt_f32_e32 vcc, s69, v81
	v_exp_f32_e32 v49, v49
	v_add_f32_e32 v6, v23, v6
	v_cndmask_b32_e32 v31, 0, v35, vcc
	v_fma_f32 v35, v11, s98, v218
	v_exp_f32_e32 v35, v35
	v_add_f32_e32 v6, v27, v6
	v_cmp_lt_f32_e32 vcc, s69, v11
	v_add_f32_e32 v6, v31, v6
	s_nop 0
	v_cndmask_b32_e32 v35, 0, v35, vcc
	v_cmp_lt_f32_e32 vcc, s69, v82
	v_add_f32_e32 v6, v35, v6
	s_nop 0
	v_cndmask_b32_e32 v49, 0, v49, vcc
	v_add_f32_e32 v6, v49, v6
	s_nop 1
	v_add_f32_dpp v6, v6, v6 row_ror:8 row_mask:0xf bank_mask:0xf bound_ctrl:1
	s_nop 1
	v_add_f32_dpp v6, v6, v6 row_ror:4 row_mask:0xf bank_mask:0xf bound_ctrl:1
	s_nop 1
	v_add_f32_dpp v6, v6, v6 row_ror:2 row_mask:0xf bank_mask:0xf bound_ctrl:1
	s_nop 1
	v_add_f32_dpp v82, v6, v6 row_ror:1 row_mask:0xf bank_mask:0xf bound_ctrl:1
	v_mov_b32_e32 v243, v82
	v_cmp_gt_f32_e32 vcc, s56, v82
	s_nop 1
	v_cndmask_b32_e64 v6, 0, 32, vcc
	v_ldexp_f32 v6, v82, v6
	v_log_f32_e32 v6, v6
	s_nop 0
	v_mul_f32_e32 v11, 0x3f317217, v6
	v_fma_f32 v11, v6, s57, -v11
	v_fmac_f32_e32 v11, 0x3377d1cf, v6
	v_fmac_f32_e32 v11, 0x3f317217, v6
	v_cmp_lt_f32_e64 s[26:27], |v6|, s58
	s_nop 1
	v_cndmask_b32_e64 v6, v6, v11, s[26:27]
	v_cndmask_b32_e32 v11, 0, v55, vcc
	v_sub_f32_e32 v6, v6, v11
	v_add_f32_e32 v80, v83, v6
	v_or_b32_e32 v6, 3, v0
	v_lshl_add_u32 v81, v6, v73, v87
	s_and_b64 vcc, exec, s[44:45]
	s_mov_b64 s[26:27], -1
	s_cbranch_vccnz .LBB0_2080
	v_lshlrev_b32_e32 v11, 2, v81
	v_add_u32_e32 v83, 48, v11
	ds_read_b32 v11, v11 offset:3632
	ds_read2st64_b32 v[84:85], v83 offset0:6 offset1:10
	s_waitcnt lgkmcnt(0)
	v_max3_f32 v83, v84, v85, v11
	v_sub_f32_e32 v84, v84, v83
	v_sub_f32_e32 v85, v85, v83
	v_mul_f32_e32 v84, 0x3fb8aa3b, v84
	v_mul_f32_e32 v85, 0x3fb8aa3b, v85
	v_sub_f32_e32 v11, v11, v83
	v_exp_f32_e32 v84, v84
	v_exp_f32_e32 v85, v85
	v_mul_f32_e32 v11, 0x3fb8aa3b, v11
	v_exp_f32_e32 v11, v11
	v_sub_f32_e32 v83, v80, v83
	v_mul_f32_e32 v83, 0x3fb8aa3b, v83
	v_exp_f32_e32 v83, v83
	v_add_f32_e32 v84, v84, v85
	v_add_f32_e32 v11, v11, v84
	v_mul_f32_e32 v11, v82, v11
	v_div_scale_f32 v82, s[26:27], v11, v11, v83
	v_rcp_f32_e32 v84, v82
	s_nop 0
	v_fma_f32 v85, -v82, v84, 1.0
	v_fmac_f32_e32 v84, v85, v84
	v_div_scale_f32 v85, vcc, v83, v11, v83
	v_mul_f32_e32 v86, v85, v84
	v_fma_f32 v87, -v82, v86, v85
	v_fmac_f32_e32 v86, v87, v84
	v_fma_f32 v82, -v82, v86, v85
	v_div_fmas_f32 v82, v82, v84, v86
	v_div_fixup_f32 v11, v82, v11, v83
	s_cbranch_execz .LBB0_2081

.LBB0_2084:
	s_mov_b64 s[52:53], -1
	v_cvt_pk_bf16_f32 v12, v12, v16
	ds_write_b16 v54, v12 offset:4688
	ds_write_b16_d16_hi v54, v12 offset:4720
	v_cvt_pk_bf16_f32 v12, v20, v24
	ds_write_b16 v54, v12 offset:4752
	ds_write_b16_d16_hi v54, v12 offset:4784
	v_cvt_pk_bf16_f32 v12, v28, v32
	ds_write_b16 v54, v12 offset:4816
	ds_write_b16_d16_hi v54, v12 offset:4848
	v_cvt_pk_bf16_f32 v12, v77, v78
	ds_write_b16 v54, v12 offset:4880
	ds_write_b16_d16_hi v54, v12 offset:4912
	v_cvt_pk_bf16_f32 v12, v79, v1
	ds_write_b16 v54, v37 offset:4656
	ds_write_b16 v54, v12 offset:4944
	ds_write_b16 v54, v37 offset:4992
	ds_write_b16_d16_hi v54, v12 offset:5024
	v_cvt_pk_bf16_f32 v1, v5, v13
	ds_write_b16 v54, v1 offset:5056
	ds_write_b16_d16_hi v54, v1 offset:5088
	v_cvt_pk_bf16_f32 v1, v17, v21
	ds_write_b16 v54, v1 offset:5120
	ds_write_b16_d16_hi v54, v1 offset:5152
	v_cvt_pk_bf16_f32 v1, v25, v29
	ds_write_b16 v54, v1 offset:5184
	ds_write_b16_d16_hi v54, v1 offset:5216
	v_cvt_pk_bf16_f32 v1, v33, v36
	ds_write_b16 v54, v1 offset:5248
	ds_write_b16_d16_hi v54, v1 offset:5280
	ds_write_b16 v54, v37 offset:5328
	v_cvt_pk_bf16_f32 v1, v14, v18
	ds_write_b16 v54, v1 offset:5360
	ds_write_b16_d16_hi v54, v1 offset:5392
	v_cvt_pk_bf16_f32 v1, v22, v26
	ds_write_b16 v54, v1 offset:5424
	ds_write_b16_d16_hi v54, v1 offset:5456
	v_cvt_pk_bf16_f32 v1, v30, v34
	ds_write_b16 v54, v1 offset:5488
	ds_write_b16_d16_hi v54, v1 offset:5520
	v_cvt_pk_bf16_f32 v1, v89, v90
	ds_write_b16 v54, v1 offset:5552
	ds_write_b16_d16_hi v54, v1 offset:5584
	v_cvt_pk_bf16_f32 v1, v91, v3
	ds_write_b16 v54, v1 offset:5616
	ds_write_b16 v54, v37 offset:5664
	ds_write_b16_d16_hi v54, v1 offset:5696
	v_cvt_pk_bf16_f32 v1, v7, v15
	ds_write_b16 v54, v1 offset:5728
	ds_write_b16_d16_hi v54, v1 offset:5760
	v_cvt_pk_bf16_f32 v1, v19, v23
	ds_write_b16 v54, v1 offset:5792
	ds_write_b16_d16_hi v54, v1 offset:5824
	v_cvt_pk_bf16_f32 v1, v27, v31
	ds_write_b16 v54, v1 offset:5856
	ds_write_b16_d16_hi v54, v1 offset:5888
	v_cvt_pk_bf16_f32 v1, v35, v49
	ds_write_b16 v54, v1 offset:5920
	ds_write_b16_d16_hi v54, v1 offset:5952
	ds_read_b128 v[100:103], v56 offset:4656
	ds_read_b128 v[104:107], v56 offset:4720
	ds_read_b128 v[108:111], v56 offset:4784
	ds_read_b128 v[112:115], v56 offset:4848
	ds_read_b128 v[116:119], v56 offset:4912
	s_waitcnt vmcnt(0) lgkmcnt(0)
	v_mfma_f32_16x16x32_bf16 v[12:15], v[100:103], v[120:123], 0
	v_mfma_f32_16x16x32_bf16 v[16:19], v[100:103], v[124:127], 0
	v_mfma_f32_16x16x32_bf16 v[28:31], v[100:103], v[128:131], 0
	v_mfma_f32_16x16x32_bf16 v[20:23], v[100:103], v[132:135], 0
	v_mfma_f32_16x16x32_bf16 v[12:15], v[104:107], v[136:139], v[12:15]
	v_mfma_f32_16x16x32_bf16 v[16:19], v[104:107], v[140:143], v[16:19]
	v_mfma_f32_16x16x32_bf16 v[28:31], v[104:107], v[144:147], v[28:31]
	v_mfma_f32_16x16x32_bf16 v[20:23], v[104:107], v[148:151], v[20:23]
	v_mfma_f32_16x16x32_bf16 v[12:15], v[108:111], v[152:155], v[12:15]
	v_mfma_f32_16x16x32_bf16 v[16:19], v[108:111], v[156:159], v[16:19]
	v_mfma_f32_16x16x32_bf16 v[28:31], v[108:111], v[160:163], v[28:31]
	v_mfma_f32_16x16x32_bf16 v[20:23], v[108:111], v[164:167], v[20:23]
	v_mfma_f32_16x16x32_bf16 v[12:15], v[112:115], v[168:171], v[12:15]
	v_mfma_f32_16x16x32_bf16 v[16:19], v[112:115], v[172:175], v[16:19]
	v_mfma_f32_16x16x32_bf16 v[28:31], v[112:115], v[180:183], v[28:31]
	v_mfma_f32_16x16x32_bf16 v[20:23], v[112:115], v[184:187], v[20:23]
	v_mfma_f32_16x16x32_bf16 v[12:15], v[116:119], v[188:191], v[12:15]
	v_mfma_f32_16x16x32_bf16 v[16:19], v[116:119], v[192:195], v[16:19]
	v_mfma_f32_16x16x32_bf16 v[28:31], v[116:119], v[196:199], v[28:31]
	v_mfma_f32_16x16x32_bf16 v[20:23], v[116:119], v[200:203], v[20:23]
	s_nop 7
	s_nop 1
	v_lshlrev_b32_e32 v1, 6, v74
	v_lshlrev_b32_e32 v36, 1, v1
	v_subrev_u32_e32 v232, s48, v42
	v_add_u32_e32 v232, v232, v36
	v_mov_b32_e32 v228, s48
	v_mov_b32_e32 v229, s49
	v_mov_b32_e32 v230, 0xee000000
	v_mov_b32_e32 v231, -1
	v_lshl_add_u64 v[228:229], v[228:229], 0, v[230:231]
	v_and_b32_e32 v116, 3, v176
	v_cmp_eq_u32_e32 vcc, 1, v116
	v_cndmask_b32_e32 v117, v0, v4, vcc
	v_cmp_eq_u32_e32 vcc, 2, v116
	v_cndmask_b32_e32 v117, v117, v2, vcc
	v_cmp_eq_u32_e32 vcc, 3, v116
	v_cndmask_b32_e32 v117, v117, v6, vcc
	v_lshlrev_b32_e32 v116, 1, v116
	v_sub_u32_e32 v118, v232, v116
	v_lshlrev_b32_e32 v220, v73, v117
	v_add_u32_e32 v220, v220, v46
	v_lshlrev_b32_e32 v220, 11, v220
	v_add_u32_e32 v220, v220, v118
	v_lshlrev_b32_e32 v220, 1, v220
	v_mov_b32_e32 v221, 0
	v_lshl_add_u64 v[220:221], v[220:221], 0, v[228:229]
	s_mov_b32 vcc_lo, 0x55555555
	s_mov_b32 vcc_hi, 0x55555555
	s_nop 1
	v_cndmask_b32_dpp v100, v13, v12, vcc quad_perm:[1,0,3,2] row_mask:0xf bank_mask:0xf
	v_cndmask_b32_dpp v102, v15, v14, vcc quad_perm:[1,0,3,2] row_mask:0xf bank_mask:0xf
	v_cndmask_b32_dpp v104, v17, v16, vcc quad_perm:[1,0,3,2] row_mask:0xf bank_mask:0xf
	v_cndmask_b32_dpp v106, v19, v18, vcc quad_perm:[1,0,3,2] row_mask:0xf bank_mask:0xf
	v_cndmask_b32_dpp v108, v29, v28, vcc quad_perm:[1,0,3,2] row_mask:0xf bank_mask:0xf
	v_cndmask_b32_dpp v110, v31, v30, vcc quad_perm:[1,0,3,2] row_mask:0xf bank_mask:0xf
	v_cndmask_b32_dpp v112, v21, v20, vcc quad_perm:[1,0,3,2] row_mask:0xf bank_mask:0xf
	v_cndmask_b32_dpp v114, v23, v22, vcc quad_perm:[1,0,3,2] row_mask:0xf bank_mask:0xf
	s_mov_b32 vcc_lo, 0xaaaaaaaa
	s_mov_b32 vcc_hi, 0xaaaaaaaa
	s_nop 1
	v_cndmask_b32_dpp v101, v12, v13, vcc quad_perm:[1,0,3,2] row_mask:0xf bank_mask:0xf
	v_cndmask_b32_dpp v103, v14, v15, vcc quad_perm:[1,0,3,2] row_mask:0xf bank_mask:0xf
	v_cndmask_b32_dpp v105, v16, v17, vcc quad_perm:[1,0,3,2] row_mask:0xf bank_mask:0xf
	v_cndmask_b32_dpp v107, v18, v19, vcc quad_perm:[1,0,3,2] row_mask:0xf bank_mask:0xf
	v_cndmask_b32_dpp v109, v28, v29, vcc quad_perm:[1,0,3,2] row_mask:0xf bank_mask:0xf
	v_cndmask_b32_dpp v111, v30, v31, vcc quad_perm:[1,0,3,2] row_mask:0xf bank_mask:0xf
	v_cndmask_b32_dpp v113, v20, v21, vcc quad_perm:[1,0,3,2] row_mask:0xf bank_mask:0xf
	v_cndmask_b32_dpp v115, v22, v23, vcc quad_perm:[1,0,3,2] row_mask:0xf bank_mask:0xf
	s_mov_b32 vcc_lo, 0x33333333
	s_mov_b32 vcc_hi, 0x33333333
	s_nop 1
	v_cndmask_b32_dpp v12, v102, v100, vcc quad_perm:[2,3,0,1] row_mask:0xf bank_mask:0xf
	v_cndmask_b32_dpp v13, v103, v101, vcc quad_perm:[2,3,0,1] row_mask:0xf bank_mask:0xf
	v_cndmask_b32_dpp v16, v106, v104, vcc quad_perm:[2,3,0,1] row_mask:0xf bank_mask:0xf
	v_cndmask_b32_dpp v17, v107, v105, vcc quad_perm:[2,3,0,1] row_mask:0xf bank_mask:0xf
	v_cndmask_b32_dpp v28, v110, v108, vcc quad_perm:[2,3,0,1] row_mask:0xf bank_mask:0xf
	v_cndmask_b32_dpp v29, v111, v109, vcc quad_perm:[2,3,0,1] row_mask:0xf bank_mask:0xf
	v_cndmask_b32_dpp v20, v114, v112, vcc quad_perm:[2,3,0,1] row_mask:0xf bank_mask:0xf
	v_cndmask_b32_dpp v21, v115, v113, vcc quad_perm:[2,3,0,1] row_mask:0xf bank_mask:0xf
	s_mov_b32 vcc_lo, 0xcccccccc
	s_mov_b32 vcc_hi, 0xcccccccc
	s_nop 1
	v_cndmask_b32_dpp v14, v100, v102, vcc quad_perm:[2,3,0,1] row_mask:0xf bank_mask:0xf
	v_cndmask_b32_dpp v15, v101, v103, vcc quad_perm:[2,3,0,1] row_mask:0xf bank_mask:0xf
	v_cndmask_b32_dpp v18, v104, v106, vcc quad_perm:[2,3,0,1] row_mask:0xf bank_mask:0xf
	v_cndmask_b32_dpp v19, v105, v107, vcc quad_perm:[2,3,0,1] row_mask:0xf bank_mask:0xf
	v_cndmask_b32_dpp v30, v108, v110, vcc quad_perm:[2,3,0,1] row_mask:0xf bank_mask:0xf
	v_cndmask_b32_dpp v31, v109, v111, vcc quad_perm:[2,3,0,1] row_mask:0xf bank_mask:0xf
	v_cndmask_b32_dpp v22, v112, v114, vcc quad_perm:[2,3,0,1] row_mask:0xf bank_mask:0xf
	v_cndmask_b32_dpp v23, v113, v115, vcc quad_perm:[2,3,0,1] row_mask:0xf bank_mask:0xf
	global_store_dwordx4 v[220:221], v[12:15], off
	global_store_dwordx4 v[220:221], v[16:19], off offset:64
	global_store_dwordx4 v[220:221], v[28:31], off offset:128
	global_store_dwordx4 v[220:221], v[20:23], off offset:192
	s_branch .LBB0_1986
